# P22 phase-0 silu table loads batched; P23 odd-mid phase re-dealt (3 SGU + 1 pool on blocks 0-127, 5 pool on blocks 128-255)
# speedup vs baseline: 1.0195x; 1.0130x over previous
.Lgemv_entry:
	s_load_dwordx8 s[12:19], s[0:1], 0x10
	s_load_dwordx4 s[20:23], s[0:1], 0x30
	s_load_dwordx2 s[34:35], s[0:1], 0x68
	s_load_dwordx2 s[30:31], s[0:1], 0x80
	s_mov_b64 s[4:5], s[64:65]
	s_mov_b64 s[28:29], s[66:67]
	v_mov_b32_e32 v22, v204
	v_readfirstlane_b32 s3, v247
	s_mul_i32 s3, s3, 0x90
	s_add_i32 s3, s3, 0x2f
	s_cmp_gt_i32 s2, s3
	s_cselect_b32 s3, 0, 0x1800
	s_nop 0
	v_cmp_gt_i32_e32 vcc, s3, v22
	s_and_saveexec_b64 s[4:5], vcc
	s_cbranch_execz .LBB0_25
	v_lshlrev_b32_e32 v4, 2, v22
	v_add_u32_e32 v2, 0x1000, v4
	v_add_u32_e32 v3, 0x2000, v4
	v_add_u32_e32 v17, 0x3000, v4
	s_waitcnt lgkmcnt(0)
	global_load_dword v5, v4, s[18:19]
	global_load_dword v6, v4, s[18:19] offset:2048
	global_load_dword v7, v2, s[18:19]
	global_load_dword v8, v2, s[18:19] offset:2048
	global_load_dword v9, v4, s[16:17]
	global_load_dword v10, v4, s[16:17] offset:2048
	global_load_dword v11, v2, s[16:17]
	global_load_dword v12, v2, s[16:17] offset:2048
	global_load_dword v13, v3, s[16:17]
	global_load_dword v14, v3, s[16:17] offset:2048
	global_load_dword v15, v17, s[16:17]
	global_load_dword v16, v17, s[16:17] offset:2048
	v_add_u32_e32 v4, 0, v4
	s_waitcnt vmcnt(11)
	v_mul_f32_e32 v18, 0xbfb8aa3b, v5
	v_exp_f32_e32 v18, v18
	s_nop 0
	v_add_f32_e32 v18, 1.0, v18
	v_rcp_f32_e32 v18, v18
	s_nop 0
	v_mul_f32_e32 v5, v5, v18
	ds_write_b32 v4, v5
	s_waitcnt vmcnt(10)
	v_mul_f32_e32 v18, 0xbfb8aa3b, v6
	v_exp_f32_e32 v18, v18
	s_nop 0
	v_add_f32_e32 v18, 1.0, v18
	v_rcp_f32_e32 v18, v18
	s_nop 0
	v_mul_f32_e32 v6, v6, v18
	ds_write_b32 v4, v6 offset:2048
	s_waitcnt vmcnt(9)
	v_mul_f32_e32 v18, 0xbfb8aa3b, v7
	v_exp_f32_e32 v18, v18
	s_nop 0
	v_add_f32_e32 v18, 1.0, v18
	v_rcp_f32_e32 v18, v18
	s_nop 0
	v_mul_f32_e32 v7, v7, v18
	ds_write_b32 v4, v7 offset:4096
	s_waitcnt vmcnt(8)
	v_mul_f32_e32 v18, 0xbfb8aa3b, v8
	v_exp_f32_e32 v18, v18
	s_nop 0
	v_add_f32_e32 v18, 1.0, v18
	v_rcp_f32_e32 v18, v18
	s_nop 0
	v_mul_f32_e32 v8, v8, v18
	ds_write_b32 v4, v8 offset:6144
	s_waitcnt vmcnt(7)
	v_mul_f32_e32 v18, 0xbfb8aa3b, v9
	v_exp_f32_e32 v18, v18
	s_nop 0
	v_add_f32_e32 v18, 1.0, v18
	v_rcp_f32_e32 v18, v18
	s_nop 0
	v_mul_f32_e32 v9, v9, v18
	ds_write_b32 v4, v9 offset:8192
	s_waitcnt vmcnt(6)
	v_mul_f32_e32 v18, 0xbfb8aa3b, v10
	v_exp_f32_e32 v18, v18
	s_nop 0
	v_add_f32_e32 v18, 1.0, v18
	v_rcp_f32_e32 v18, v18
	s_nop 0
	v_mul_f32_e32 v10, v10, v18
	ds_write_b32 v4, v10 offset:10240
	s_waitcnt vmcnt(5)
	v_mul_f32_e32 v18, 0xbfb8aa3b, v11
	v_exp_f32_e32 v18, v18
	s_nop 0
	v_add_f32_e32 v18, 1.0, v18
	v_rcp_f32_e32 v18, v18
	s_nop 0
	v_mul_f32_e32 v11, v11, v18
	ds_write_b32 v4, v11 offset:12288
	s_waitcnt vmcnt(4)
	v_mul_f32_e32 v18, 0xbfb8aa3b, v12
	v_exp_f32_e32 v18, v18
	s_nop 0
	v_add_f32_e32 v18, 1.0, v18
	v_rcp_f32_e32 v18, v18
	s_nop 0
	v_mul_f32_e32 v12, v12, v18
	ds_write_b32 v4, v12 offset:14336
	s_waitcnt vmcnt(3)
	v_mul_f32_e32 v18, 0xbfb8aa3b, v13
	v_exp_f32_e32 v18, v18
	s_nop 0
	v_add_f32_e32 v18, 1.0, v18
	v_rcp_f32_e32 v18, v18
	s_nop 0
	v_mul_f32_e32 v13, v13, v18
	ds_write_b32 v4, v13 offset:16384
	s_waitcnt vmcnt(2)
	v_mul_f32_e32 v18, 0xbfb8aa3b, v14
	v_exp_f32_e32 v18, v18
	s_nop 0
	v_add_f32_e32 v18, 1.0, v18
	v_rcp_f32_e32 v18, v18
	s_nop 0
	v_mul_f32_e32 v14, v14, v18
	ds_write_b32 v4, v14 offset:18432
	s_waitcnt vmcnt(1)
	v_mul_f32_e32 v18, 0xbfb8aa3b, v15
	v_exp_f32_e32 v18, v18
	s_nop 0
	v_add_f32_e32 v18, 1.0, v18
	v_rcp_f32_e32 v18, v18
	s_nop 0
	v_mul_f32_e32 v15, v15, v18
	ds_write_b32 v4, v15 offset:20480
	s_waitcnt vmcnt(0)
	v_mul_f32_e32 v18, 0xbfb8aa3b, v16
	v_exp_f32_e32 v18, v18
	s_nop 0
	v_add_f32_e32 v18, 1.0, v18
	v_rcp_f32_e32 v18, v18
	s_nop 0
	v_mul_f32_e32 v16, v16, v18
	ds_write_b32 v4, v16 offset:22528

.LBB0_301:
	v_readlane_b32 s18, v255, 21
	s_lshl_b32 s18, s18, 10
	s_bitcmp1_b32 s35, 0
	v_writelane_b32 v255, s18, 22
	s_nop 1
	v_writelane_b32 v255, s19, 23
	s_cselect_b64 s[18:19], -1, 0
	s_cmp_ge_i32 s22, s52
	s_cselect_b64 s[22:23], -1, 0
	s_and_b64 s[0:1], s[22:23], s[0:1]
	v_cndmask_b32_e64 v0, 0, 1, s[0:1]
	s_and_b64 vcc, exec, s[18:19]
	v_cmp_ne_u32_e64 s[36:37], 1, v0
	s_cbranch_vccz .LBB0_314
	s_and_b64 vcc, exec, s[36:37]
	s_cbranch_vccnz .LBB0_428
	s_mov_b64 s[0:1], s[64:65]
	s_mov_b64 s[18:19], s[66:67]
	v_readlane_b32 s64, v255, 22
	v_readlane_b32 s0, v253, 54
	s_add_u32 s24, s18, 0xa048000
	v_readlane_b32 s1, v253, 55
	v_readlane_b32 s65, v255, 23
	v_readlane_b32 s48, v254, 52
	s_addc_u32 s25, s19, 0
	s_andn2_b64 vcc, exec, s[0:1]
	s_mov_b32 s65, s61
	v_readlane_b32 s66, v253, 56
	v_readlane_b32 s67, v253, 57
	s_cmp_lt_u32 s2, 0x80
	s_cbranch_scc1 .Lom_deal_a
	s_sub_i32 s66, s2, 0x80
	s_mul_i32 s66, s66, 5
	s_addk_i32 s66, 0x80
	s_mov_b32 s67, 5
	s_branch .Lom_deal_done
.Lom_deal_a:
	s_mov_b32 s66, s2
	s_mov_b32 s67, 1
.Lom_deal_done:
	s_movk_i32 s46, 0x1000
	s_mov_b32 s47, 0x800000
	v_readlane_b32 s49, v254, 53
	s_cbranch_vccnz .LBB0_315
	v_readlane_b32 s28, v254, 60
	s_lshl_b64 s[0:1], s[64:65], 2
	v_readlane_b32 s30, v254, 62
	v_readlane_b32 s31, v254, 63
	s_add_u32 s22, s30, s0
	s_addc_u32 s23, s31, s1
	s_add_u32 s30, s18, 0x1df98000
	v_readlane_b32 s0, v255, 21
	s_addc_u32 s31, s19, 0
	s_lshl_b32 s38, s0, 2
	s_mov_b32 s39, s2
	v_readlane_b32 s29, v254, 61
	s_cmp_gt_u32 s2, 0x7f
	s_cbranch_scc1 .LBB0_315
	s_branch .LBB0_306
.LBB0_305:
	s_or_b64 exec, exec, s[0:1]
	s_addk_i32 s39, 0x80
	s_cmpk_gt_i32 s39, 0x17f
	s_cbranch_scc1 .LBB0_315
